# mods_phase: the 36 silu(c) inputs a thread stages into LDS are fetched with all 36 loads in flight instead of one per round trip
# speedup vs baseline: 1.1029x; 1.0079x over previous
; DI float silu_f(float x) { return x * __builtin_amdgcn_rcpf(1.f + __expf(-x)); }
; DI void mods_phase(const P& p, char* smem, int vb, int nvb) {
;     ...
;   bool loaded = false;
;   for (int job = vb; job < 576; job += nvb) {
;     if (!loaded) {
;       for (int i = t; i < 9 * 1024; i += NTHR) {
;         const float v = i < 8192 ? p.c[i] : p.c_ctx[i - 8192];
;         sc[i] = silu_f(v);
;       }
;       loaded = true;
;       __syncthreads();
.LBB0_21:
	s_and_b64 vcc, exec, s[18:19]
	s_cbranch_vccnz .LBB0_26
	s_and_saveexec_b64 s[18:19], s[6:7]
	s_cbranch_execz .LBB0_25
	s_mov_b64 s[20:21], 0x1000
	v_mov_b64_e32 v[0:1], v[114:115]
	global_load_dword v224, v[0:1], off
	global_load_dword v225, v[0:1], off offset:1024
	global_load_dword v226, v[0:1], off offset:2048
	global_load_dword v227, v[0:1], off offset:3072
	v_lshl_add_u64 v[0:1], v[0:1], 0, s[20:21]
	global_load_dword v228, v[0:1], off
	global_load_dword v229, v[0:1], off offset:1024
	global_load_dword v230, v[0:1], off offset:2048
	global_load_dword v231, v[0:1], off offset:3072
	v_lshl_add_u64 v[0:1], v[0:1], 0, s[20:21]
	global_load_dword v232, v[0:1], off
	global_load_dword v233, v[0:1], off offset:1024
	global_load_dword v234, v[0:1], off offset:2048
	global_load_dword v235, v[0:1], off offset:3072
	v_lshl_add_u64 v[0:1], v[0:1], 0, s[20:21]
	global_load_dword v236, v[0:1], off
	global_load_dword v237, v[0:1], off offset:1024
	global_load_dword v238, v[0:1], off offset:2048
	global_load_dword v239, v[0:1], off offset:3072
	v_lshl_add_u64 v[0:1], v[0:1], 0, s[20:21]
	global_load_dword v240, v[0:1], off
	global_load_dword v241, v[0:1], off offset:1024
	global_load_dword v242, v[0:1], off offset:2048
	global_load_dword v243, v[0:1], off offset:3072
	v_lshl_add_u64 v[0:1], v[0:1], 0, s[20:21]
	global_load_dword v244, v[0:1], off
	global_load_dword v245, v[0:1], off offset:1024
	global_load_dword v246, v[0:1], off offset:2048
	global_load_dword v247, v[0:1], off offset:3072
	v_lshl_add_u64 v[0:1], v[0:1], 0, s[20:21]
	global_load_dword v248, v[0:1], off
	global_load_dword v249, v[0:1], off offset:1024
	global_load_dword v250, v[0:1], off offset:2048
	global_load_dword v251, v[0:1], off offset:3072
	v_lshl_add_u64 v[0:1], v[0:1], 0, s[20:21]
	global_load_dword v252, v[0:1], off
	global_load_dword v253, v[0:1], off offset:1024
	global_load_dword v254, v[0:1], off offset:2048
	global_load_dword v255, v[0:1], off offset:3072
	v_add_u32_e32 v110, 0x2000, v108
	v_lshl_add_u64 v[4:5], v[110:111], 2, s[42:43]
	v_lshl_add_u64 v[4:5], v[4:5], 0, s[14:15]
	global_load_dword v0, v[4:5], off
	global_load_dword v1, v[4:5], off offset:1024
	global_load_dword v2, v[4:5], off offset:2048
	global_load_dword v3, v[4:5], off offset:3072
	s_waitcnt vmcnt(34)
	v_mul_f32_e32 v4, 0xbfb8aa3b, v224
	v_mul_f32_e32 v5, 0xbfb8aa3b, v225
	v_exp_f32_e32 v4, v4
	v_exp_f32_e32 v5, v5
	v_add_f32_e32 v4, 1.0, v4
	v_add_f32_e32 v5, 1.0, v5
	v_rcp_f32_e32 v4, v4
	v_rcp_f32_e32 v5, v5
	v_mul_f32_e32 v224, v224, v4
	v_mul_f32_e32 v225, v225, v5
	ds_write_b32 v125, v224
	ds_write_b32 v125, v225 offset:1024
	s_waitcnt vmcnt(32)
	v_mul_f32_e32 v4, 0xbfb8aa3b, v226
	v_mul_f32_e32 v5, 0xbfb8aa3b, v227
	v_exp_f32_e32 v4, v4
	v_exp_f32_e32 v5, v5
	v_add_f32_e32 v4, 1.0, v4
	v_add_f32_e32 v5, 1.0, v5
	v_rcp_f32_e32 v4, v4
	v_rcp_f32_e32 v5, v5
	v_mul_f32_e32 v226, v226, v4
	v_mul_f32_e32 v227, v227, v5
	ds_write_b32 v125, v226 offset:2048
	ds_write_b32 v125, v227 offset:3072
	s_waitcnt vmcnt(30)
	v_mul_f32_e32 v4, 0xbfb8aa3b, v228
	v_mul_f32_e32 v5, 0xbfb8aa3b, v229
	v_exp_f32_e32 v4, v4
	v_exp_f32_e32 v5, v5
	v_add_f32_e32 v4, 1.0, v4
	v_add_f32_e32 v5, 1.0, v5
	v_rcp_f32_e32 v4, v4
	v_rcp_f32_e32 v5, v5
	v_mul_f32_e32 v228, v228, v4
	v_mul_f32_e32 v229, v229, v5
	ds_write_b32 v125, v228 offset:4096
	ds_write_b32 v125, v229 offset:5120
	s_waitcnt vmcnt(28)
	v_mul_f32_e32 v4, 0xbfb8aa3b, v230
	v_mul_f32_e32 v5, 0xbfb8aa3b, v231
	v_exp_f32_e32 v4, v4
	v_exp_f32_e32 v5, v5
	v_add_f32_e32 v4, 1.0, v4
	v_add_f32_e32 v5, 1.0, v5
	v_rcp_f32_e32 v4, v4
	v_rcp_f32_e32 v5, v5
	v_mul_f32_e32 v230, v230, v4
	v_mul_f32_e32 v231, v231, v5
	ds_write_b32 v125, v230 offset:6144
	ds_write_b32 v125, v231 offset:7168
	s_waitcnt vmcnt(26)
	v_mul_f32_e32 v4, 0xbfb8aa3b, v232
	v_mul_f32_e32 v5, 0xbfb8aa3b, v233
	v_exp_f32_e32 v4, v4
	v_exp_f32_e32 v5, v5
	v_add_f32_e32 v4, 1.0, v4
	v_add_f32_e32 v5, 1.0, v5
	v_rcp_f32_e32 v4, v4
	v_rcp_f32_e32 v5, v5
	v_mul_f32_e32 v232, v232, v4
	v_mul_f32_e32 v233, v233, v5
	ds_write_b32 v125, v232 offset:8192
	ds_write_b32 v125, v233 offset:9216
	s_waitcnt vmcnt(24)
	v_mul_f32_e32 v4, 0xbfb8aa3b, v234
	v_mul_f32_e32 v5, 0xbfb8aa3b, v235
	v_exp_f32_e32 v4, v4
	v_exp_f32_e32 v5, v5
	v_add_f32_e32 v4, 1.0, v4
	v_add_f32_e32 v5, 1.0, v5
	v_rcp_f32_e32 v4, v4
	v_rcp_f32_e32 v5, v5
	v_mul_f32_e32 v234, v234, v4
	v_mul_f32_e32 v235, v235, v5
	ds_write_b32 v125, v234 offset:10240
	ds_write_b32 v125, v235 offset:11264
	s_waitcnt vmcnt(22)
; DI float silu_f(float x) { return x * __builtin_amdgcn_rcpf(1.f + __expf(-x)); }
; DI void mods_phase(const P& p, char* smem, int vb, int nvb) {
;     ...
;       for (int i = t; i < 9 * 1024; i += NTHR) {
;         const float v = i < 8192 ? p.c[i] : p.c_ctx[i - 8192];
;         sc[i] = silu_f(v);
;       }
	v_mul_f32_e32 v4, 0xbfb8aa3b, v236
	v_mul_f32_e32 v5, 0xbfb8aa3b, v237
	v_exp_f32_e32 v4, v4
	v_exp_f32_e32 v5, v5
	v_add_f32_e32 v4, 1.0, v4
	v_add_f32_e32 v5, 1.0, v5
	v_rcp_f32_e32 v4, v4
	v_rcp_f32_e32 v5, v5
	v_mul_f32_e32 v236, v236, v4
	v_mul_f32_e32 v237, v237, v5
	ds_write_b32 v125, v236 offset:12288
	ds_write_b32 v125, v237 offset:13312
	s_waitcnt vmcnt(20)
	v_mul_f32_e32 v4, 0xbfb8aa3b, v238
	v_mul_f32_e32 v5, 0xbfb8aa3b, v239
	v_exp_f32_e32 v4, v4
	v_exp_f32_e32 v5, v5
	v_add_f32_e32 v4, 1.0, v4
	v_add_f32_e32 v5, 1.0, v5
	v_rcp_f32_e32 v4, v4
	v_rcp_f32_e32 v5, v5
	v_mul_f32_e32 v238, v238, v4
	v_mul_f32_e32 v239, v239, v5
	ds_write_b32 v125, v238 offset:14336
	ds_write_b32 v125, v239 offset:15360
	s_waitcnt vmcnt(18)
	v_mul_f32_e32 v4, 0xbfb8aa3b, v240
	v_mul_f32_e32 v5, 0xbfb8aa3b, v241
	v_exp_f32_e32 v4, v4
	v_exp_f32_e32 v5, v5
	v_add_f32_e32 v4, 1.0, v4
	v_add_f32_e32 v5, 1.0, v5
	v_rcp_f32_e32 v4, v4
	v_rcp_f32_e32 v5, v5
	v_mul_f32_e32 v240, v240, v4
	v_mul_f32_e32 v241, v241, v5
	ds_write_b32 v125, v240 offset:16384
	ds_write_b32 v125, v241 offset:17408
	s_waitcnt vmcnt(16)
	v_mul_f32_e32 v4, 0xbfb8aa3b, v242
	v_mul_f32_e32 v5, 0xbfb8aa3b, v243
	v_exp_f32_e32 v4, v4
	v_exp_f32_e32 v5, v5
	v_add_f32_e32 v4, 1.0, v4
	v_add_f32_e32 v5, 1.0, v5
	v_rcp_f32_e32 v4, v4
	v_rcp_f32_e32 v5, v5
	v_mul_f32_e32 v242, v242, v4
	v_mul_f32_e32 v243, v243, v5
	ds_write_b32 v125, v242 offset:18432
	ds_write_b32 v125, v243 offset:19456
	s_waitcnt vmcnt(14)
	v_mul_f32_e32 v4, 0xbfb8aa3b, v244
	v_mul_f32_e32 v5, 0xbfb8aa3b, v245
	v_exp_f32_e32 v4, v4
	v_exp_f32_e32 v5, v5
	v_add_f32_e32 v4, 1.0, v4
	v_add_f32_e32 v5, 1.0, v5
	v_rcp_f32_e32 v4, v4
	v_rcp_f32_e32 v5, v5
	v_mul_f32_e32 v244, v244, v4
	v_mul_f32_e32 v245, v245, v5
	ds_write_b32 v125, v244 offset:20480
	ds_write_b32 v125, v245 offset:21504
	s_waitcnt vmcnt(12)
	v_mul_f32_e32 v4, 0xbfb8aa3b, v246
	v_mul_f32_e32 v5, 0xbfb8aa3b, v247
	v_exp_f32_e32 v4, v4
	v_exp_f32_e32 v5, v5
	v_add_f32_e32 v4, 1.0, v4
	v_add_f32_e32 v5, 1.0, v5
	v_rcp_f32_e32 v4, v4
	v_rcp_f32_e32 v5, v5
	v_mul_f32_e32 v246, v246, v4
	v_mul_f32_e32 v247, v247, v5
	ds_write_b32 v125, v246 offset:22528
	ds_write_b32 v125, v247 offset:23552
	s_waitcnt vmcnt(10)
	v_mul_f32_e32 v4, 0xbfb8aa3b, v248
	v_mul_f32_e32 v5, 0xbfb8aa3b, v249
	v_exp_f32_e32 v4, v4
	v_exp_f32_e32 v5, v5
	v_add_f32_e32 v4, 1.0, v4
	v_add_f32_e32 v5, 1.0, v5
	v_rcp_f32_e32 v4, v4
	v_rcp_f32_e32 v5, v5
	v_mul_f32_e32 v248, v248, v4
	v_mul_f32_e32 v249, v249, v5
	ds_write_b32 v125, v248 offset:24576
	ds_write_b32 v125, v249 offset:25600
	s_waitcnt vmcnt(8)
	v_mul_f32_e32 v4, 0xbfb8aa3b, v250
	v_mul_f32_e32 v5, 0xbfb8aa3b, v251
	v_exp_f32_e32 v4, v4
	v_exp_f32_e32 v5, v5
	v_add_f32_e32 v4, 1.0, v4
	v_add_f32_e32 v5, 1.0, v5
	v_rcp_f32_e32 v4, v4
	v_rcp_f32_e32 v5, v5
	v_mul_f32_e32 v250, v250, v4
	v_mul_f32_e32 v251, v251, v5
	ds_write_b32 v125, v250 offset:26624
	ds_write_b32 v125, v251 offset:27648
	s_waitcnt vmcnt(6)
	v_mul_f32_e32 v4, 0xbfb8aa3b, v252
	v_mul_f32_e32 v5, 0xbfb8aa3b, v253
	v_exp_f32_e32 v4, v4
	v_exp_f32_e32 v5, v5
	v_add_f32_e32 v4, 1.0, v4
	v_add_f32_e32 v5, 1.0, v5
	v_rcp_f32_e32 v4, v4
	v_rcp_f32_e32 v5, v5
	v_mul_f32_e32 v252, v252, v4
	v_mul_f32_e32 v253, v253, v5
	ds_write_b32 v125, v252 offset:28672
	ds_write_b32 v125, v253 offset:29696
	s_waitcnt vmcnt(4)
	v_mul_f32_e32 v4, 0xbfb8aa3b, v254
	v_mul_f32_e32 v5, 0xbfb8aa3b, v255
	v_exp_f32_e32 v4, v4
	v_exp_f32_e32 v5, v5
	v_add_f32_e32 v4, 1.0, v4
	v_add_f32_e32 v5, 1.0, v5
	v_rcp_f32_e32 v4, v4
	v_rcp_f32_e32 v5, v5
	v_mul_f32_e32 v254, v254, v4
	v_mul_f32_e32 v255, v255, v5
	ds_write_b32 v125, v254 offset:30720
	ds_write_b32 v125, v255 offset:31744
	s_waitcnt vmcnt(2)
	v_mul_f32_e32 v4, 0xbfb8aa3b, v0
	v_mul_f32_e32 v5, 0xbfb8aa3b, v1
	v_exp_f32_e32 v4, v4
	v_exp_f32_e32 v5, v5
	v_add_f32_e32 v4, 1.0, v4
	v_add_f32_e32 v5, 1.0, v5
	v_rcp_f32_e32 v4, v4
	v_rcp_f32_e32 v5, v5
	v_mul_f32_e32 v0, v0, v4
	v_mul_f32_e32 v1, v1, v5
	ds_write_b32 v125, v0 offset:32768
	ds_write_b32 v125, v1 offset:33792
	s_waitcnt vmcnt(0)
	v_mul_f32_e32 v4, 0xbfb8aa3b, v2
	v_mul_f32_e32 v5, 0xbfb8aa3b, v3
	v_exp_f32_e32 v4, v4
	v_exp_f32_e32 v5, v5
	v_add_f32_e32 v4, 1.0, v4
	v_add_f32_e32 v5, 1.0, v5
	v_rcp_f32_e32 v4, v4
	v_rcp_f32_e32 v5, v5
	v_mul_f32_e32 v2, v2, v4
	v_mul_f32_e32 v3, v3, v5
	ds_write_b32 v125, v2 offset:34816
	ds_write_b32 v125, v3 offset:35840
